# ph5 table conversion: the fp8 table rows are stored write-through (sc1) so the grid barrier's L2 write-back after the step has less to flush; on top of v062
# speedup vs baseline: 1.0053x; 1.0053x over previous
.LBB0_172:
	v_mov_b32_e32 v2, 0xc0
	v_lshl_add_u64 v[26:27], s[8:9], 0, v[20:21]
	v_add_u32_e32 v2, 0, v2
	v_add_u32_e32 v2, 0x20200, v2
	ds_read_b32 v3, v2
	ds_read_b32 v2, v2 offset:4
	s_waitcnt lgkmcnt(0)
	v_readfirstlane_b32 s2, v3
	s_waitcnt lgkmcnt(0)
	v_readfirstlane_b32 s3, v2
	s_add_u32 s2, s8, s2
	s_addc_u32 s3, s9, s3
	v_lshl_add_u64 v[2:3], s[2:3], 0, v[22:23]
	global_load_dwordx4 v[6:9], v[2:3], off offset:48
	global_load_dwordx4 v[10:13], v[2:3], off offset:32
	global_load_dwordx4 v[14:17], v[2:3], off offset:16
	s_nop 0
	global_load_dwordx4 v[2:5], v[2:3], off
	s_waitcnt vmcnt(0)
	v_max_f32_e64 v29, |v8|, |v8|
	s_waitcnt vmcnt(1)
	v_max_f32_e64 v28, |v16|, |v16|
	s_waitcnt vmcnt(0)
	v_max_f32_e64 v18, |v5|, |v5|
	v_max_f32_e64 v19, |v4|, |v4|
	v_max_f32_e32 v18, v19, v18
	v_max_f32_e64 v19, |v17|, |v17|
	v_max_f32_e32 v19, v28, v19
	v_max3_f32 v18, |v2|, |v3|, v18
	v_max3_f32 v19, |v14|, |v15|, v19
	v_max3_f32 v18, v18, 0, v19
	v_max_f32_e64 v19, |v13|, |v13|
	v_max_f32_e64 v28, |v12|, |v12|
	v_max_f32_e32 v19, v28, v19
	v_max_f32_e64 v28, |v9|, |v9|
	v_max_f32_e32 v28, v29, v28
	v_max3_f32 v19, |v10|, |v11|, v19
	v_max3_f32 v28, |v6|, |v7|, v28
	v_max3_f32 v18, v18, v19, v28
	s_nop 1
	v_mov_b32_dpp v19, v18 quad_perm:[1,0,3,2] row_mask:0xf bank_mask:0xf bound_ctrl:1
	v_max_f32_e32 v19, v19, v19
	v_max_f32_e32 v18, v18, v19
	s_nop 1
	v_mov_b32_dpp v19, v18 quad_perm:[2,3,0,1] row_mask:0xf bank_mask:0xf bound_ctrl:1
	v_max_f32_e32 v19, v19, v19
	v_max_f32_e32 v18, v18, v19
	s_nop 1
	v_mov_b32_dpp v19, v18 row_half_mirror row_mask:0xf bank_mask:0xf bound_ctrl:1
	v_max_f32_e32 v19, v19, v19
	v_max_f32_e32 v18, v18, v19
	s_nop 1
	v_mov_b32_dpp v19, v18 row_mirror row_mask:0xf bank_mask:0xf bound_ctrl:1
	v_max_f32_e32 v19, v19, v19
	v_max_f32_e32 v18, v18, v19
	s_nop 0
	v_readlane_b32 s13, v18, 32
	v_readlane_b32 s23, v18, 48
	v_readlane_b32 s2, v18, 0
	v_readlane_b32 s3, v18, 16
	v_max_f32_e64 v18, s23, s23
	v_max_f32_e64 v19, s13, s13
	v_max_f32_e32 v18, v19, v18
	v_mov_b32_e32 v19, s3
	v_max3_f32 v18, s2, v19, v18
	s_mov_b32 s13, 0x43e00000
	v_div_scale_f32 v19, s[30:31], v18, v18, s13
	v_rcp_f32_e32 v28, v19
	v_cmp_lt_f32_e64 s[2:3], 0, v18
	v_fma_f32 v29, -v19, v28, 1.0
	v_fmac_f32_e32 v28, v29, v28
	v_div_scale_f32 v29, vcc, s13, v18, s13
	v_mul_f32_e32 v30, v29, v28
	v_fma_f32 v31, -v19, v30, v29
	v_fmac_f32_e32 v30, v31, v28
	v_fma_f32 v19, -v19, v30, v29
	v_div_fmas_f32 v19, v19, v28, v30
	v_div_fixup_f32 v19, v19, v18, s13
	v_cndmask_b32_e64 v19, 0, v19, s[2:3]
	v_mul_f32_e32 v28, v2, v19
	v_mul_f32_e32 v3, v3, v19
	v_mov_b32_e32 v2, v155
	v_cvt_pk_fp8_f32 v2, v28, v3
	v_mul_f32_e32 v3, v4, v19
	v_mul_f32_e32 v4, v5, v19
	v_mul_f32_e32 v5, v15, v19
	v_cvt_pk_fp8_f32 v2, v3, v4 op_sel:[0,0,1]
	v_mul_f32_e32 v4, v14, v19
	v_mov_b32_e32 v3, v155
	v_cvt_pk_fp8_f32 v3, v4, v5
	v_mul_f32_e32 v4, v16, v19
	v_mul_f32_e32 v5, v17, v19
	v_mul_f32_e32 v6, v6, v19
	v_cvt_pk_fp8_f32 v3, v4, v5 op_sel:[0,0,1]
	v_mul_f32_e32 v5, v10, v19
	v_mul_f32_e32 v10, v11, v19
	v_mov_b32_e32 v4, v155
	v_cvt_pk_fp8_f32 v4, v5, v10
	v_mul_f32_e32 v5, v12, v19
	v_mul_f32_e32 v10, v13, v19
	v_mul_f32_e32 v7, v7, v19
	v_cvt_pk_fp8_f32 v4, v5, v10 op_sel:[0,0,1]
	v_mov_b32_e32 v5, v155
	v_cvt_pk_fp8_f32 v5, v6, v7
	v_mul_f32_e32 v6, v8, v19
	v_mul_f32_e32 v7, v9, v19
	v_lshl_add_u64 v[28:29], s[8:9], 0, v[24:25]
	v_cvt_pk_fp8_f32 v5, v6, v7 op_sel:[0,0,1]
	v_add_co_u32_e32 v6, vcc, 0x22000000, v28
	s_nop 1
	v_addc_co_u32_e32 v7, vcc, 0, v29, vcc
	global_store_dwordx4 v[6:7], v[2:5], off sc1
	s_and_saveexec_b64 s[2:3], s[0:1]
	s_cbranch_execz .LBB0_174
	v_add_co_u32_e32 v2, vcc, 0x2a000000, v26
	v_mul_f32_e32 v4, 0x3b124925, v18
	s_nop 0
	v_addc_co_u32_e32 v3, vcc, 0, v27, vcc
	global_store_dword v[2:3], v4, off
.LBB0_174:
	s_or_b64 exec, exec, s[2:3]
	v_mov_b32_e32 v2, 0xc8
	s_nop 0
	v_add_u32_e32 v2, 0, v2
	v_add_u32_e32 v2, 0x20200, v2
	ds_read_b32 v3, v2
	ds_read_b32 v2, v2 offset:4
	s_waitcnt lgkmcnt(1)
	v_readfirstlane_b32 s2, v3
	s_waitcnt lgkmcnt(0)
	v_readfirstlane_b32 s3, v2
	s_add_u32 s2, s8, s2
	s_addc_u32 s3, s9, s3
	v_lshl_add_u64 v[6:7], s[2:3], 0, v[22:23]
	global_load_dwordx4 v[2:5], v[6:7], off offset:48
	global_load_dwordx4 v[8:11], v[6:7], off offset:32
	global_load_dwordx4 v[12:15], v[6:7], off offset:16
	global_load_dwordx4 v[16:19], v[6:7], off
	s_waitcnt vmcnt(3)
	v_max_f32_e64 v31, |v4|, |v4|
	s_waitcnt vmcnt(1)
	v_max_f32_e64 v30, |v14|, |v14|
	s_waitcnt vmcnt(0)
	v_max_f32_e64 v6, |v19|, |v19|
	v_max_f32_e64 v7, |v18|, |v18|
	v_max_f32_e32 v6, v7, v6
	v_max_f32_e64 v7, |v15|, |v15|
	v_max_f32_e32 v7, v30, v7
	v_max3_f32 v6, |v16|, |v17|, v6
	v_max3_f32 v7, |v12|, |v13|, v7
	v_max3_f32 v6, v6, 0, v7
	v_max_f32_e64 v7, |v11|, |v11|
	v_max_f32_e64 v30, |v10|, |v10|
	v_max_f32_e32 v7, v30, v7
	v_max_f32_e64 v30, |v5|, |v5|
	v_max_f32_e32 v30, v31, v30
	v_max3_f32 v7, |v8|, |v9|, v7
	v_max3_f32 v30, |v2|, |v3|, v30
	v_max3_f32 v6, v6, v7, v30
	s_nop 1
	v_mov_b32_dpp v7, v6 quad_perm:[1,0,3,2] row_mask:0xf bank_mask:0xf bound_ctrl:1
	v_max_f32_e32 v7, v7, v7
	v_max_f32_e32 v6, v6, v7
	s_nop 1
	v_mov_b32_dpp v7, v6 quad_perm:[2,3,0,1] row_mask:0xf bank_mask:0xf bound_ctrl:1
	v_max_f32_e32 v7, v7, v7
	v_max_f32_e32 v6, v6, v7
	s_nop 1
	v_mov_b32_dpp v7, v6 row_half_mirror row_mask:0xf bank_mask:0xf bound_ctrl:1
	v_max_f32_e32 v7, v7, v7
	v_max_f32_e32 v6, v6, v7
	s_nop 1
	v_mov_b32_dpp v7, v6 row_mirror row_mask:0xf bank_mask:0xf bound_ctrl:1
	v_max_f32_e32 v7, v7, v7
	v_max_f32_e32 v6, v6, v7
	s_nop 0
	v_readlane_b32 s13, v6, 32
	v_readlane_b32 s23, v6, 48
	v_readlane_b32 s2, v6, 0
	v_readlane_b32 s3, v6, 16
	v_max_f32_e64 v6, s23, s23
	v_max_f32_e64 v7, s13, s13
	v_max_f32_e32 v6, v7, v6
	v_mov_b32_e32 v7, s3
	v_max3_f32 v30, s2, v7, v6
	s_mov_b32 s13, 0x43e00000
	v_div_scale_f32 v6, s[30:31], v30, v30, s13
	v_rcp_f32_e32 v7, v6
	v_cmp_lt_f32_e64 s[2:3], 0, v30
	v_fma_f32 v31, -v6, v7, 1.0
	v_fmac_f32_e32 v7, v31, v7
	v_div_scale_f32 v31, vcc, s13, v30, s13
	v_mul_f32_e32 v32, v31, v7
	v_fma_f32 v33, -v6, v32, v31
	v_fmac_f32_e32 v32, v33, v7
	v_fma_f32 v6, -v6, v32, v31
	v_div_fmas_f32 v6, v6, v7, v32
	v_div_fixup_f32 v6, v6, v30, s13
	v_cndmask_b32_e64 v31, 0, v6, s[2:3]
	v_mul_f32_e32 v7, v16, v31
	v_mul_f32_e32 v16, v17, v31
	v_mov_b32_e32 v6, v155
	v_cvt_pk_fp8_f32 v6, v7, v16
	v_mul_f32_e32 v7, v18, v31
	v_mul_f32_e32 v16, v19, v31
	v_mul_f32_e32 v12, v12, v31
	v_cvt_pk_fp8_f32 v6, v7, v16 op_sel:[0,0,1]
	v_mul_f32_e32 v13, v13, v31
	v_mov_b32_e32 v7, v155
	v_cvt_pk_fp8_f32 v7, v12, v13
	v_mul_f32_e32 v12, v14, v31
	v_mul_f32_e32 v13, v15, v31
	v_mul_f32_e32 v9, v9, v31
	v_cvt_pk_fp8_f32 v7, v12, v13 op_sel:[0,0,1]
	v_mul_f32_e32 v12, v8, v31
	v_mov_b32_e32 v8, v155
	v_cvt_pk_fp8_f32 v8, v12, v9
	v_mul_f32_e32 v9, v10, v31
	v_mul_f32_e32 v10, v11, v31
	v_mul_f32_e32 v2, v2, v31
	v_cvt_pk_fp8_f32 v8, v9, v10 op_sel:[0,0,1]
	v_mul_f32_e32 v3, v3, v31
	v_mov_b32_e32 v9, v155
	v_cvt_pk_fp8_f32 v9, v2, v3
	v_mul_f32_e32 v2, v4, v31
	v_mul_f32_e32 v3, v5, v31
	v_cvt_pk_fp8_f32 v9, v2, v3 op_sel:[0,0,1]
	v_add_co_u32_e32 v2, vcc, 0x26000000, v28
	s_nop 1
	v_addc_co_u32_e32 v3, vcc, 0, v29, vcc
	global_store_dwordx4 v[2:3], v[6:9], off sc1
	s_and_saveexec_b64 s[2:3], s[0:1]
	s_cbranch_execz .LBB0_171
	v_add_co_u32_e32 v2, vcc, 0x2a000000, v26
	v_mul_f32_e32 v4, 0x3b124925, v30
	s_nop 0
	v_addc_co_u32_e32 v3, vcc, 0, v27, vcc
	global_store_dword v[2:3], v4, off offset:4
	s_branch .LBB0_171

.LBB0_201:
	v_mov_b32_e32 v2, 0xc0
	v_lshl_add_u64 v[26:27], s[4:5], 0, v[20:21]
	v_add_u32_e32 v2, 0, v2
	v_add_u32_e32 v2, 0x20200, v2
	ds_read_b32 v3, v2
	ds_read_b32 v2, v2 offset:4
	s_waitcnt lgkmcnt(0)
	v_readfirstlane_b32 s2, v3
	v_readfirstlane_b32 s3, v2
	s_add_u32 s2, s4, s2
	s_addc_u32 s3, s5, s3
	v_lshl_add_u64 v[2:3], s[2:3], 0, v[22:23]
	global_load_dwordx4 v[6:9], v[2:3], off offset:48
	global_load_dwordx4 v[10:13], v[2:3], off offset:32
	global_load_dwordx4 v[14:17], v[2:3], off offset:16
	s_nop 0
	global_load_dwordx4 v[2:5], v[2:3], off
	s_waitcnt vmcnt(0)
	v_max_f32_e64 v29, |v8|, |v8|
	v_max_f32_e64 v28, |v16|, |v16|
	v_max_f32_e64 v18, |v5|, |v5|
	v_max_f32_e64 v19, |v4|, |v4|
	v_max_f32_e32 v18, v19, v18
	v_max_f32_e64 v19, |v17|, |v17|
	v_max_f32_e32 v19, v28, v19
	v_max3_f32 v18, |v2|, |v3|, v18
	v_max3_f32 v19, |v14|, |v15|, v19
	v_max3_f32 v18, v18, 0, v19
	v_max_f32_e64 v19, |v13|, |v13|
	v_max_f32_e64 v28, |v12|, |v12|
	v_max_f32_e32 v19, v28, v19
	v_max_f32_e64 v28, |v9|, |v9|
	v_max_f32_e32 v28, v29, v28
	v_max3_f32 v19, |v10|, |v11|, v19
	v_max3_f32 v28, |v6|, |v7|, v28
	v_max3_f32 v18, v18, v19, v28
	s_nop 1
	v_mov_b32_dpp v19, v18 quad_perm:[1,0,3,2] row_mask:0xf bank_mask:0xf bound_ctrl:1
	v_max_f32_e32 v19, v19, v19
	v_max_f32_e32 v18, v18, v19
	s_nop 1
	v_mov_b32_dpp v19, v18 quad_perm:[2,3,0,1] row_mask:0xf bank_mask:0xf bound_ctrl:1
	v_max_f32_e32 v19, v19, v19
	v_max_f32_e32 v18, v18, v19
	s_nop 1
	v_mov_b32_dpp v19, v18 row_half_mirror row_mask:0xf bank_mask:0xf bound_ctrl:1
	v_max_f32_e32 v19, v19, v19
	v_max_f32_e32 v18, v18, v19
	s_nop 1
	v_mov_b32_dpp v19, v18 row_mirror row_mask:0xf bank_mask:0xf bound_ctrl:1
	v_max_f32_e32 v19, v19, v19
	v_max_f32_e32 v18, v18, v19
	s_nop 0
	v_readlane_b32 s9, v18, 32
	v_readlane_b32 s19, v18, 48
	v_readlane_b32 s2, v18, 0
	v_readlane_b32 s3, v18, 16
	v_max_f32_e64 v18, s19, s19
	v_max_f32_e64 v19, s9, s9
	v_max_f32_e32 v18, v19, v18
	v_mov_b32_e32 v19, s3
	v_max3_f32 v18, s2, v19, v18
	s_mov_b32 s9, 0x43e00000
	v_div_scale_f32 v19, s[20:21], v18, v18, s9
	v_rcp_f32_e32 v28, v19
	v_cmp_lt_f32_e64 s[2:3], 0, v18
	v_fma_f32 v29, -v19, v28, 1.0
	v_fmac_f32_e32 v28, v29, v28
	v_div_scale_f32 v29, vcc, s9, v18, s9
	v_mul_f32_e32 v30, v29, v28
	v_fma_f32 v31, -v19, v30, v29
	v_fmac_f32_e32 v30, v31, v28
	v_fma_f32 v19, -v19, v30, v29
	v_div_fmas_f32 v19, v19, v28, v30
	v_div_fixup_f32 v19, v19, v18, s9
	v_cndmask_b32_e64 v19, 0, v19, s[2:3]
	v_mul_f32_e32 v28, v2, v19
	v_mul_f32_e32 v3, v3, v19
	v_mov_b32_e32 v2, v155
	v_cvt_pk_fp8_f32 v2, v28, v3
	v_mul_f32_e32 v3, v4, v19
	v_mul_f32_e32 v4, v5, v19
	v_mul_f32_e32 v5, v15, v19
	v_cvt_pk_fp8_f32 v2, v3, v4 op_sel:[0,0,1]
	v_mul_f32_e32 v4, v14, v19
	v_mov_b32_e32 v3, v155
	v_cvt_pk_fp8_f32 v3, v4, v5
	v_mul_f32_e32 v4, v16, v19
	v_mul_f32_e32 v5, v17, v19
	v_mul_f32_e32 v6, v6, v19
	v_cvt_pk_fp8_f32 v3, v4, v5 op_sel:[0,0,1]
	v_mul_f32_e32 v5, v10, v19
	v_mul_f32_e32 v10, v11, v19
	v_mov_b32_e32 v4, v155
	v_cvt_pk_fp8_f32 v4, v5, v10
	v_mul_f32_e32 v5, v12, v19
	v_mul_f32_e32 v10, v13, v19
	v_mul_f32_e32 v7, v7, v19
	v_cvt_pk_fp8_f32 v4, v5, v10 op_sel:[0,0,1]
	v_mov_b32_e32 v5, v155
	v_cvt_pk_fp8_f32 v5, v6, v7
	v_mul_f32_e32 v6, v8, v19
	v_mul_f32_e32 v7, v9, v19
	v_lshl_add_u64 v[28:29], s[4:5], 0, v[24:25]
	v_cvt_pk_fp8_f32 v5, v6, v7 op_sel:[0,0,1]
	v_add_co_u32_e32 v6, vcc, 0x22000000, v28
	s_nop 1
	v_addc_co_u32_e32 v7, vcc, 0, v29, vcc
	global_store_dwordx4 v[6:7], v[2:5], off sc1
	s_and_saveexec_b64 s[2:3], s[0:1]
	s_cbranch_execz .LBB0_203
	v_add_co_u32_e32 v2, vcc, 0x2a000000, v26
	v_mul_f32_e32 v4, 0x3b124925, v18
	s_nop 0
	v_addc_co_u32_e32 v3, vcc, 0, v27, vcc
	global_store_dword v[2:3], v4, off
.LBB0_203:
	s_or_b64 exec, exec, s[2:3]
	v_mov_b32_e32 v2, 0xc8
	s_nop 0
	v_add_u32_e32 v2, 0, v2
	v_add_u32_e32 v2, 0x20200, v2
	ds_read_b32 v3, v2
	ds_read_b32 v2, v2 offset:4
	s_waitcnt lgkmcnt(1)
	v_readfirstlane_b32 s2, v3
	s_waitcnt lgkmcnt(0)
	v_readfirstlane_b32 s3, v2
	s_add_u32 s2, s4, s2
	s_addc_u32 s3, s5, s3
	v_lshl_add_u64 v[6:7], s[2:3], 0, v[22:23]
	global_load_dwordx4 v[2:5], v[6:7], off offset:48
	global_load_dwordx4 v[8:11], v[6:7], off offset:32
	global_load_dwordx4 v[12:15], v[6:7], off offset:16
	global_load_dwordx4 v[16:19], v[6:7], off
	s_waitcnt vmcnt(3)
	v_max_f32_e64 v31, |v4|, |v4|
	s_waitcnt vmcnt(1)
	v_max_f32_e64 v30, |v14|, |v14|
	s_waitcnt vmcnt(0)
	v_max_f32_e64 v6, |v19|, |v19|
	v_max_f32_e64 v7, |v18|, |v18|
	v_max_f32_e32 v6, v7, v6
	v_max_f32_e64 v7, |v15|, |v15|
	v_max_f32_e32 v7, v30, v7
	v_max3_f32 v6, |v16|, |v17|, v6
	v_max3_f32 v7, |v12|, |v13|, v7
	v_max3_f32 v6, v6, 0, v7
	v_max_f32_e64 v7, |v11|, |v11|
	v_max_f32_e64 v30, |v10|, |v10|
	v_max_f32_e32 v7, v30, v7
	v_max_f32_e64 v30, |v5|, |v5|
	v_max_f32_e32 v30, v31, v30
	v_max3_f32 v7, |v8|, |v9|, v7
	v_max3_f32 v30, |v2|, |v3|, v30
	v_max3_f32 v6, v6, v7, v30
	s_nop 1
	v_mov_b32_dpp v7, v6 quad_perm:[1,0,3,2] row_mask:0xf bank_mask:0xf bound_ctrl:1
	v_max_f32_e32 v7, v7, v7
	v_max_f32_e32 v6, v6, v7
	s_nop 1
	v_mov_b32_dpp v7, v6 quad_perm:[2,3,0,1] row_mask:0xf bank_mask:0xf bound_ctrl:1
	v_max_f32_e32 v7, v7, v7
	v_max_f32_e32 v6, v6, v7
	s_nop 1
	v_mov_b32_dpp v7, v6 row_half_mirror row_mask:0xf bank_mask:0xf bound_ctrl:1
	v_max_f32_e32 v7, v7, v7
	v_max_f32_e32 v6, v6, v7
	s_nop 1
	v_mov_b32_dpp v7, v6 row_mirror row_mask:0xf bank_mask:0xf bound_ctrl:1
	v_max_f32_e32 v7, v7, v7
	v_max_f32_e32 v6, v6, v7
	s_nop 0
	v_readlane_b32 s9, v6, 32
	v_readlane_b32 s19, v6, 48
	v_readlane_b32 s2, v6, 0
	v_readlane_b32 s3, v6, 16
	v_max_f32_e64 v6, s19, s19
	v_max_f32_e64 v7, s9, s9
	v_max_f32_e32 v6, v7, v6
	v_mov_b32_e32 v7, s3
	v_max3_f32 v30, s2, v7, v6
	s_mov_b32 s9, 0x43e00000
	v_div_scale_f32 v6, s[20:21], v30, v30, s9
	v_rcp_f32_e32 v7, v6
	v_cmp_lt_f32_e64 s[2:3], 0, v30
	v_fma_f32 v31, -v6, v7, 1.0
	v_fmac_f32_e32 v7, v31, v7
	v_div_scale_f32 v31, vcc, s9, v30, s9
	v_mul_f32_e32 v32, v31, v7
	v_fma_f32 v33, -v6, v32, v31
	v_fmac_f32_e32 v32, v33, v7
	v_fma_f32 v6, -v6, v32, v31
	v_div_fmas_f32 v6, v6, v7, v32
	v_div_fixup_f32 v6, v6, v30, s9
	v_cndmask_b32_e64 v31, 0, v6, s[2:3]
	v_mul_f32_e32 v7, v16, v31
	v_mul_f32_e32 v16, v17, v31
	v_mov_b32_e32 v6, v155
	v_cvt_pk_fp8_f32 v6, v7, v16
	v_mul_f32_e32 v7, v18, v31
	v_mul_f32_e32 v16, v19, v31
	v_mul_f32_e32 v12, v12, v31
	v_cvt_pk_fp8_f32 v6, v7, v16 op_sel:[0,0,1]
	v_mul_f32_e32 v13, v13, v31
	v_mov_b32_e32 v7, v155
	v_cvt_pk_fp8_f32 v7, v12, v13
	v_mul_f32_e32 v12, v14, v31
	v_mul_f32_e32 v13, v15, v31
	v_mul_f32_e32 v9, v9, v31
	v_cvt_pk_fp8_f32 v7, v12, v13 op_sel:[0,0,1]
	v_mul_f32_e32 v12, v8, v31
	v_mov_b32_e32 v8, v155
	v_cvt_pk_fp8_f32 v8, v12, v9
	v_mul_f32_e32 v9, v10, v31
	v_mul_f32_e32 v10, v11, v31
	v_mul_f32_e32 v2, v2, v31
	v_cvt_pk_fp8_f32 v8, v9, v10 op_sel:[0,0,1]
	v_mul_f32_e32 v3, v3, v31
	v_mov_b32_e32 v9, v155
	v_cvt_pk_fp8_f32 v9, v2, v3
	v_mul_f32_e32 v2, v4, v31
	v_mul_f32_e32 v3, v5, v31
	v_cvt_pk_fp8_f32 v9, v2, v3 op_sel:[0,0,1]
	v_add_co_u32_e32 v2, vcc, 0x26000000, v28
	s_nop 1
	v_addc_co_u32_e32 v3, vcc, 0, v29, vcc
	global_store_dwordx4 v[2:3], v[6:9], off sc1
	s_and_saveexec_b64 s[2:3], s[0:1]
	s_cbranch_execz .LBB0_200
	v_add_co_u32_e32 v2, vcc, 0x2a000000, v26
	v_mul_f32_e32 v4, 0x3b124925, v30
	s_nop 0
	v_addc_co_u32_e32 v3, vcc, 0, v27, vcc
	global_store_dword v[2:3], v4, off offset:4
	s_branch .LBB0_200
